# same flag-in-data panel exchange, poll bound raised to 4M iterations (as the baseline's counter spin)
# baseline (speedup 1.0000x reference)
.LBB0_563:
	s_waitcnt lgkmcnt(0)
	s_barrier
	s_and_b64 vcc, exec, s[2:3]
	s_cbranch_vccnz .LBB0_565
	v_lshlrev_b64 v[96:97], 5, v[96:97]
	v_lshl_add_u64 v[96:97], s[12:13], 0, v[96:97]
	s_mov_b32 s100, 0x400000
	s_sleep 4
